# attention steady loop: rare O-rescale blocks moved out of line so the common path has no taken branch (on top of aligned loop heads)
# speedup vs baseline: 1.0040x; 1.0025x over previous
; #define WAIT_BAR(N) asm volatile("s_waitcnt vmcnt(" #N ") lgkmcnt(0)\n\ts_barrier":::"memory")
;   #define RESC() do{ if(resc){ asm volatile("s_waitcnt lgkmcnt(0)":::"memory"); \
;       _Pragma("unroll") for(int d_=0;d_<2;++d_) _Pragma("unroll") for(int r=0;r<16;++r)o[d_][r]*=wsf[crow(r,hi)]; } }while(0)
;   #define ROT() do{sl_prev=sl_cur;sl_cur=sl_next;sl_next=(sl_next==(NSLOT-1)*SLOTB)?0:sl_next+SLOTB;}while(0)
; template<int THRL> __device__ __forceinline__ void attn_unit(int b,int h,int hv,int qb,const bf16*Q,const bf16*__restrict__ K,const bf16*__restrict__ V,bf16*O,char*shm){
;     ...
;     STEP(pB0,pB1,pA0,pA1,t,true,true,true);     WAIT_BAR(2); RESC(); ROT();
.LBB0_1427:
	s_waitcnt lgkmcnt(14)
	v_mfma_f32_32x32x16_bf16 v[48:63], v[172:175], v[208:211], v[48:63]
	v_exp_f32_e32 v128, v128
	v_exp_f32_e32 v129, v129
	v_exp_f32_e32 v130, v130
	v_exp_f32_e32 v131, v131
	s_waitcnt lgkmcnt(12)
	v_mfma_f32_32x32x16_bf16 v[32:47], v[172:175], v[96:99], v[32:47]
	v_exp_f32_e32 v132, v132
	v_exp_f32_e32 v133, v133
	v_exp_f32_e32 v134, v134
	v_exp_f32_e32 v135, v135
	v_add_u32_e32 v0, s50, v240
	ds_read_b128 v[92:95], v0
	ds_read_b128 v[200:203], v0 offset:512
	s_waitcnt lgkmcnt(12)
	v_mfma_f32_32x32x16_bf16 v[48:63], v[164:167], v[2:5], v[48:63]
	v_exp_f32_e32 v136, v136
	v_exp_f32_e32 v137, v137
	v_exp_f32_e32 v138, v138
	v_exp_f32_e32 v139, v139
	ds_read_b128 v[204:207], v0 offset:2048
	ds_read_b128 v[196:199], v0 offset:2560
	s_waitcnt lgkmcnt(12)
	v_mfma_f32_32x32x16_bf16 v[32:47], v[164:167], v[6:9], v[32:47]
	v_exp_f32_e32 v140, v140
	v_exp_f32_e32 v141, v141
	v_exp_f32_e32 v142, v142
	v_exp_f32_e32 v143, v143
	ds_read_b128 v[192:195], v0 offset:4096
	ds_read_b128 v[188:191], v0 offset:4608
	s_waitcnt lgkmcnt(12)
	v_mfma_f32_32x32x16_bf16 v[48:63], v[156:159], v[10:13], v[48:63]
	v_exp_f32_e32 v112, v112
	v_exp_f32_e32 v113, v113
	v_exp_f32_e32 v114, v114
	v_exp_f32_e32 v115, v115
	ds_read_b128 v[184:187], v0 offset:6144
	ds_read_b128 v[180:183], v0 offset:6656
	s_waitcnt lgkmcnt(12)
	v_mfma_f32_32x32x16_bf16 v[32:47], v[156:159], v[80:83], v[32:47]
	v_exp_f32_e32 v116, v116
	v_exp_f32_e32 v117, v117
	v_exp_f32_e32 v118, v118
	v_exp_f32_e32 v119, v119
	s_waitcnt lgkmcnt(10)
	v_mfma_f32_32x32x16_bf16 v[48:63], v[148:151], v[84:87], v[48:63]
	v_exp_f32_e32 v120, v120
	v_exp_f32_e32 v121, v121
	v_exp_f32_e32 v122, v122
	v_exp_f32_e32 v123, v123
	s_waitcnt lgkmcnt(8)
	v_mfma_f32_32x32x16_bf16 v[32:47], v[148:151], v[88:91], v[32:47]
	v_exp_f32_e32 v124, v124
	v_exp_f32_e32 v125, v125
	v_exp_f32_e32 v126, v126
	v_exp_f32_e32 v127, v127
	s_waitcnt vmcnt(2) lgkmcnt(0)
	s_barrier
	s_andn2_b64 vcc, exec, s[0:1]
	v_add_u32_e32 v0, s59, v242
	s_cbranch_vccz .Lresc_a

; #define WAIT_BAR(N) asm volatile("s_waitcnt vmcnt(" #N ") lgkmcnt(0)\n\ts_barrier":::"memory")
;   #define RESC() do{ if(resc){ asm volatile("s_waitcnt lgkmcnt(0)":::"memory"); \
;       _Pragma("unroll") for(int d_=0;d_<2;++d_) _Pragma("unroll") for(int r=0;r<16;++r)o[d_][r]*=wsf[crow(r,hi)]; } }while(0)
;   #define ROT() do{sl_prev=sl_cur;sl_cur=sl_next;sl_next=(sl_next==(NSLOT-1)*SLOTB)?0:sl_next+SLOTB;}while(0)
; template<int THRL> __device__ __forceinline__ void attn_unit(int b,int h,int hv,int qb,const bf16*Q,const bf16*__restrict__ K,const bf16*__restrict__ V,bf16*O,char*shm){
;     ...
;     STEP(pA0,pA1,pB0,pB1,t+1,true,true,true);   WAIT_BAR(2); RESC(); ROT();
.LBB0_1430:
	s_waitcnt lgkmcnt(14)
	v_mfma_f32_32x32x16_bf16 v[48:63], v[172:175], v[176:179], v[48:63]
	v_exp_f32_e32 v96, v96
	v_exp_f32_e32 v97, v97
	v_exp_f32_e32 v98, v98
	v_exp_f32_e32 v99, v99
	s_waitcnt lgkmcnt(12)
	v_mfma_f32_32x32x16_bf16 v[32:47], v[172:175], v[128:131], v[32:47]
	v_exp_f32_e32 v100, v100
	v_exp_f32_e32 v101, v101
	v_exp_f32_e32 v102, v102
	v_exp_f32_e32 v103, v103
	v_add_u32_e32 v14, s73, v240
	ds_read_b128 v[204:207], v14
	ds_read_b128 v[200:203], v14 offset:512
	s_waitcnt lgkmcnt(12)
	v_mfma_f32_32x32x16_bf16 v[48:63], v[164:167], v[2:5], v[48:63]
	v_exp_f32_e32 v104, v104
	v_exp_f32_e32 v105, v105
	v_exp_f32_e32 v106, v106
	v_exp_f32_e32 v107, v107
	ds_read_b128 v[196:199], v14 offset:2048
	ds_read_b128 v[192:195], v14 offset:2560
	s_waitcnt lgkmcnt(12)
	v_mfma_f32_32x32x16_bf16 v[32:47], v[164:167], v[6:9], v[32:47]
	v_exp_f32_e32 v108, v108
	v_exp_f32_e32 v109, v109
	v_exp_f32_e32 v110, v110
	v_exp_f32_e32 v111, v111
	ds_read_b128 v[188:191], v14 offset:4096
	ds_read_b128 v[184:187], v14 offset:4608
	s_waitcnt lgkmcnt(12)
	v_mfma_f32_32x32x16_bf16 v[48:63], v[156:159], v[10:13], v[48:63]
	v_exp_f32_e32 v80, v80
	v_exp_f32_e32 v81, v81
	v_exp_f32_e32 v82, v82
	v_exp_f32_e32 v83, v83
	ds_read_b128 v[180:183], v14 offset:6144
	ds_read_b128 v[176:179], v14 offset:6656
	s_waitcnt lgkmcnt(12)
	v_mfma_f32_32x32x16_bf16 v[32:47], v[156:159], v[112:115], v[32:47]
	v_exp_f32_e32 v84, v84
	v_exp_f32_e32 v85, v85
	v_exp_f32_e32 v86, v86
	v_exp_f32_e32 v87, v87
	s_waitcnt lgkmcnt(10)
	v_mfma_f32_32x32x16_bf16 v[48:63], v[148:151], v[116:119], v[48:63]
	v_exp_f32_e32 v88, v88
	v_exp_f32_e32 v89, v89
	v_exp_f32_e32 v90, v90
	v_exp_f32_e32 v91, v91
	s_waitcnt lgkmcnt(8)
	v_mfma_f32_32x32x16_bf16 v[32:47], v[148:151], v[120:123], v[32:47]
	v_exp_f32_e32 v92, v92
	v_exp_f32_e32 v93, v93
	v_exp_f32_e32 v94, v94
	v_exp_f32_e32 v95, v95
	s_waitcnt vmcnt(2) lgkmcnt(0)
	s_barrier
	s_andn2_b64 vcc, exec, s[0:1]
	s_cbranch_vccz .Lresc_b

; #define WAIT_BAR(N) asm volatile("s_waitcnt vmcnt(" #N ") lgkmcnt(0)\n\ts_barrier":::"memory")
;   #define RESC() do{ if(resc){ asm volatile("s_waitcnt lgkmcnt(0)":::"memory"); \
;       _Pragma("unroll") for(int d_=0;d_<2;++d_) _Pragma("unroll") for(int r=0;r<16;++r)o[d_][r]*=wsf[crow(r,hi)]; } }while(0)
;   #define ROT() do{sl_prev=sl_cur;sl_cur=sl_next;sl_next=(sl_next==(NSLOT-1)*SLOTB)?0:sl_next+SLOTB;}while(0)
; template<int THRL> __device__ __forceinline__ void attn_unit(int b,int h,int hv,int qb,const bf16*Q,const bf16*__restrict__ K,const bf16*__restrict__ V,bf16*O,char*shm){
;     ...
;   for(;t+5<NT;t+=2){
;     STEP(pB0,pB1,pA0,pA1,t,true,true,true);     WAIT_BAR(2); RESC(); ROT();
;     STEP(pA0,pA1,pB0,pB1,t+1,true,true,true);   WAIT_BAR(2); RESC(); ROT();
;   }
.Lresc_a:
	s_waitcnt lgkmcnt(0)
	ds_read_b128 v[2:5], v0 offset:49248
	ds_read_b128 v[6:9], v0 offset:49216
	ds_read_b128 v[10:13], v0 offset:49184
	ds_read_b128 v[80:83], v0 offset:49152
	s_waitcnt lgkmcnt(3)
	v_pk_mul_f32 v[60:61], v[60:61], v[2:3]
	s_waitcnt lgkmcnt(2)
	v_pk_mul_f32 v[56:57], v[56:57], v[6:7]
	s_waitcnt lgkmcnt(1)
	v_pk_mul_f32 v[52:53], v[52:53], v[10:11]
	v_pk_mul_f32 v[62:63], v[62:63], v[4:5]
	v_pk_mul_f32 v[58:59], v[58:59], v[8:9]
	v_pk_mul_f32 v[54:55], v[54:55], v[12:13]
	s_waitcnt lgkmcnt(0)
	v_pk_mul_f32 v[50:51], v[50:51], v[82:83]
	v_pk_mul_f32 v[48:49], v[48:49], v[80:81]
	v_pk_mul_f32 v[44:45], v[44:45], v[2:3]
	v_pk_mul_f32 v[40:41], v[40:41], v[6:7]
	v_pk_mul_f32 v[36:37], v[36:37], v[10:11]
	v_pk_mul_f32 v[46:47], v[46:47], v[4:5]
	v_pk_mul_f32 v[42:43], v[42:43], v[8:9]
	v_pk_mul_f32 v[38:39], v[38:39], v[12:13]
	v_pk_mul_f32 v[34:35], v[34:35], v[82:83]
	v_pk_mul_f32 v[32:33], v[32:33], v[80:81]
	s_branch .LBB0_1429
.Lresc_b:
	s_waitcnt lgkmcnt(0)
	ds_read_b128 v[2:5], v0 offset:49248
	ds_read_b128 v[6:9], v0 offset:49216
	ds_read_b128 v[10:13], v0 offset:49184
	ds_read_b128 v[112:115], v0 offset:49152
	s_waitcnt lgkmcnt(3)
	v_pk_mul_f32 v[60:61], v[60:61], v[2:3]
	s_waitcnt lgkmcnt(2)
	v_pk_mul_f32 v[56:57], v[56:57], v[6:7]
	s_waitcnt lgkmcnt(1)
	v_pk_mul_f32 v[52:53], v[52:53], v[10:11]
	v_pk_mul_f32 v[62:63], v[62:63], v[4:5]
	v_pk_mul_f32 v[58:59], v[58:59], v[8:9]
	v_pk_mul_f32 v[54:55], v[54:55], v[12:13]
	s_waitcnt lgkmcnt(0)
	v_pk_mul_f32 v[50:51], v[50:51], v[114:115]
	v_pk_mul_f32 v[48:49], v[48:49], v[112:113]
	v_pk_mul_f32 v[44:45], v[44:45], v[2:3]
	v_pk_mul_f32 v[40:41], v[40:41], v[6:7]
	v_pk_mul_f32 v[36:37], v[36:37], v[10:11]
	v_pk_mul_f32 v[46:47], v[46:47], v[4:5]
	v_pk_mul_f32 v[42:43], v[42:43], v[8:9]
	v_pk_mul_f32 v[38:39], v[38:39], v[12:13]
	v_pk_mul_f32 v[34:35], v[34:35], v[114:115]
	v_pk_mul_f32 v[32:33], v[32:33], v[112:113]
	s_branch .LBB0_1432
